# P8 K-loop rotated like P1 (LDS reads first after each barrier, scalar bookkeeping behind)
# speedup vs baseline: 1.0055x; 1.0003x over previous
.LBB0_1763:
	s_ashr_i32 s23, s22, 31
	s_lshl_b64 s[24:25], s[22:23], 19
	s_add_u32 s24, s68, s24
	s_addc_u32 s25, s69, s25
	s_and_b64 s[26:27], s[6:7], exec
	s_cselect_b32 s23, s25, s47
	s_cselect_b32 s56, s24, s46
	s_ashr_i32 s21, s20, 31
	s_lshl_b64 s[26:27], s[20:21], 19
	s_add_u32 s26, s0, s26
	s_addc_u32 s27, s1, s27
	s_and_b64 s[48:49], s[6:7], exec
	s_cselect_b32 s57, s27, s31
	s_cselect_b32 s58, s26, s30
	s_lshl_b32 s21, s28, 8
	v_add_u32_e32 v6, s21, v218
	s_add_u32 s28, s46, 0x3ff80
	v_ashrrev_i32_e32 v7, 31, v6
	s_addc_u32 s29, s47, 0
	v_lshl_add_u64 v[214:215], v[6:7], 4, s[8:9]
	s_add_u32 s59, s30, 0
	v_mov_b32_e32 v6, 0
	s_addc_u32 s60, s31, 0
	s_mov_b32 s61, -2
	v_mov_b32_e32 v7, v6
	v_mov_b32_e32 v8, v6
	v_mov_b32_e32 v9, v6
	v_mov_b32_e32 v14, v6
	v_mov_b32_e32 v15, v6
	v_mov_b32_e32 v16, v6
	v_mov_b32_e32 v17, v6
	v_mov_b32_e32 v22, v6
	v_mov_b32_e32 v23, v6
	v_mov_b32_e32 v24, v6
	v_mov_b32_e32 v25, v6
	v_mov_b32_e32 v30, v6
	v_mov_b32_e32 v31, v6
	v_mov_b32_e32 v32, v6
	v_mov_b32_e32 v33, v6
	v_mov_b32_e32 v38, v6
	v_mov_b32_e32 v39, v6
	v_mov_b32_e32 v40, v6
	v_mov_b32_e32 v41, v6
	v_mov_b32_e32 v46, v6
	v_mov_b32_e32 v47, v6
	v_mov_b32_e32 v48, v6
	v_mov_b32_e32 v49, v6
	v_mov_b32_e32 v54, v6
	v_mov_b32_e32 v55, v6
	v_mov_b32_e32 v56, v6
	v_mov_b32_e32 v57, v6
	v_mov_b32_e32 v62, v6
	v_mov_b32_e32 v63, v6
	v_mov_b32_e32 v64, v6
	v_mov_b32_e32 v65, v6
	v_mov_b32_e32 v10, v6
	v_mov_b32_e32 v11, v6
	v_mov_b32_e32 v12, v6
	v_mov_b32_e32 v13, v6
	v_mov_b32_e32 v18, v6
	v_mov_b32_e32 v19, v6
	v_mov_b32_e32 v20, v6
	v_mov_b32_e32 v21, v6
	v_mov_b32_e32 v26, v6
	v_mov_b32_e32 v27, v6
	v_mov_b32_e32 v28, v6
	v_mov_b32_e32 v29, v6
	v_mov_b32_e32 v34, v6
	v_mov_b32_e32 v35, v6
	v_mov_b32_e32 v36, v6
	v_mov_b32_e32 v37, v6
	v_mov_b32_e32 v42, v6
	v_mov_b32_e32 v43, v6
	v_mov_b32_e32 v44, v6
	v_mov_b32_e32 v45, v6
	v_mov_b32_e32 v50, v6
	v_mov_b32_e32 v51, v6
	v_mov_b32_e32 v52, v6
	v_mov_b32_e32 v53, v6
	v_mov_b32_e32 v58, v6
	v_mov_b32_e32 v59, v6
	v_mov_b32_e32 v60, v6
	v_mov_b32_e32 v61, v6
	v_mov_b32_e32 v66, v6
	v_mov_b32_e32 v67, v6
	v_mov_b32_e32 v68, v6
	v_mov_b32_e32 v69, v6
	v_mov_b32_e32 v70, v6
	v_mov_b32_e32 v71, v6
	v_mov_b32_e32 v72, v6
	v_mov_b32_e32 v73, v6
	v_mov_b32_e32 v78, v6
	v_mov_b32_e32 v79, v6
	v_mov_b32_e32 v80, v6
	v_mov_b32_e32 v81, v6
	v_mov_b32_e32 v86, v6
	v_mov_b32_e32 v87, v6
	v_mov_b32_e32 v88, v6
	v_mov_b32_e32 v89, v6
	v_mov_b32_e32 v94, v6
	v_mov_b32_e32 v95, v6
	v_mov_b32_e32 v96, v6
	v_mov_b32_e32 v97, v6
	v_mov_b32_e32 v102, v6
	v_mov_b32_e32 v103, v6
	v_mov_b32_e32 v104, v6
	v_mov_b32_e32 v105, v6
	v_mov_b32_e32 v110, v6
	v_mov_b32_e32 v111, v6
	v_mov_b32_e32 v112, v6
	v_mov_b32_e32 v113, v6
	v_mov_b32_e32 v118, v6
	v_mov_b32_e32 v119, v6
	v_mov_b32_e32 v120, v6
	v_mov_b32_e32 v121, v6
	v_mov_b32_e32 v126, v6
	v_mov_b32_e32 v127, v6
	v_mov_b32_e32 v128, v6
	v_mov_b32_e32 v129, v6
	v_mov_b32_e32 v74, v6
	v_mov_b32_e32 v75, v6
	v_mov_b32_e32 v76, v6
	v_mov_b32_e32 v77, v6
	v_mov_b32_e32 v82, v6
	v_mov_b32_e32 v83, v6
	v_mov_b32_e32 v84, v6
	v_mov_b32_e32 v85, v6
	v_mov_b32_e32 v90, v6
	v_mov_b32_e32 v91, v6
	v_mov_b32_e32 v92, v6
	v_mov_b32_e32 v93, v6
	v_mov_b32_e32 v98, v6
	v_mov_b32_e32 v99, v6
	v_mov_b32_e32 v100, v6
	v_mov_b32_e32 v101, v6
	v_mov_b32_e32 v106, v6
	v_mov_b32_e32 v107, v6
	v_mov_b32_e32 v108, v6
	v_mov_b32_e32 v109, v6
	v_mov_b32_e32 v114, v6
	v_mov_b32_e32 v115, v6
	v_mov_b32_e32 v116, v6
	v_mov_b32_e32 v117, v6
	v_mov_b32_e32 v122, v6
	v_mov_b32_e32 v123, v6
	v_mov_b32_e32 v124, v6
	v_mov_b32_e32 v125, v6
	v_mov_b32_e32 v130, v6
	v_mov_b32_e32 v131, v6
	v_mov_b32_e32 v132, v6
	v_mov_b32_e32 v133, v6
	s_branch .LBB0_1766

.LBB0_1766:
	v_add_u32_e32 v146, s53, v217
	v_add_u32_e32 v162, s54, v217
	ds_read_b128 v[134:137], v146
	ds_read_b128 v[138:141], v146 offset:1024
	ds_read_b128 v[142:145], v146 offset:2048
	ds_read_b128 v[146:149], v146 offset:3072
	ds_read_b128 v[150:153], v162
	ds_read_b128 v[154:157], v162 offset:1024
	ds_read_b128 v[158:161], v162 offset:2048
	ds_read_b128 v[162:165], v162 offset:3072
	ds_read_b128 v[166:169], v220
	ds_read_b128 v[170:173], v220 offset:1024
	ds_read_b128 v[174:177], v220 offset:2048
	ds_read_b128 v[178:181], v220 offset:3072
	ds_read_b128 v[182:185], v220 offset:4096
	ds_read_b128 v[186:189], v220 offset:5120
	ds_read_b128 v[190:193], v220 offset:6144
	ds_read_b128 v[194:197], v220 offset:7168
	s_add_u32 s28, s28, 0x100
	s_addc_u32 s29, s29, 0
	s_add_u32 s59, s59, 0x100
	s_addc_u32 s60, s60, 0
	s_cmp_eq_u32 s61, 12
	s_cselect_b64 s[30:31], -1, 0
	s_cbranch_scc0 .LBB0_1768
	global_load_dwordx4 v[2:5], v[214:215], off
.LBB0_1768:
	s_add_u32 s48, s28, 0xfffc0080
	s_addc_u32 s49, s29, -1
	s_and_b64 s[46:47], s[30:31], exec
	s_cselect_b32 s49, s23, s49
	s_cselect_b32 s48, s56, s48
	s_cselect_b32 s47, s57, s60
	s_cselect_b32 s46, s58, s59
	s_add_i32 m0, s40, 0xc000
	s_nop 0
	global_load_lds_dwordx4 v206, s[28:29]
	s_add_i32 m0, s40, 0xe000
	s_nop 0
	global_load_lds_dwordx4 v208, s[28:29]
	s_waitcnt vmcnt(8)
	s_waitcnt lgkmcnt(0)
	s_barrier
	s_setprio 1
	s_waitcnt lgkmcnt(0)
	v_mfma_f32_16x16x32_bf16 v[130:133], v[134:137], v[166:169], v[130:133]
	v_mfma_f32_16x16x32_bf16 v[122:125], v[142:145], v[166:169], v[122:125]
	v_mfma_f32_16x16x32_bf16 v[114:117], v[134:137], v[174:177], v[114:117]
	v_mfma_f32_16x16x32_bf16 v[106:109], v[142:145], v[174:177], v[106:109]
	v_mfma_f32_16x16x32_bf16 v[98:101], v[134:137], v[182:185], v[98:101]
	v_mfma_f32_16x16x32_bf16 v[90:93], v[142:145], v[182:185], v[90:93]
	v_mfma_f32_16x16x32_bf16 v[82:85], v[134:137], v[190:193], v[82:85]
	v_mfma_f32_16x16x32_bf16 v[74:77], v[142:145], v[190:193], v[74:77]
	v_mfma_f32_16x16x32_bf16 v[130:133], v[138:141], v[170:173], v[130:133]
	v_mfma_f32_16x16x32_bf16 v[122:125], v[146:149], v[170:173], v[122:125]
	v_mfma_f32_16x16x32_bf16 v[114:117], v[138:141], v[178:181], v[114:117]
	v_mfma_f32_16x16x32_bf16 v[106:109], v[146:149], v[178:181], v[106:109]
	v_mfma_f32_16x16x32_bf16 v[98:101], v[138:141], v[186:189], v[98:101]
	v_mfma_f32_16x16x32_bf16 v[90:93], v[146:149], v[186:189], v[90:93]
	v_mfma_f32_16x16x32_bf16 v[82:85], v[138:141], v[194:197], v[82:85]
	v_mfma_f32_16x16x32_bf16 v[74:77], v[146:149], v[194:197], v[74:77]
	s_setprio 0
	s_setprio 1
	v_mfma_f32_16x16x32_bf16 v[126:129], v[150:153], v[166:169], v[126:129]
	v_mfma_f32_16x16x32_bf16 v[118:121], v[158:161], v[166:169], v[118:121]
	v_mfma_f32_16x16x32_bf16 v[110:113], v[150:153], v[174:177], v[110:113]
	v_mfma_f32_16x16x32_bf16 v[102:105], v[158:161], v[174:177], v[102:105]
	v_mfma_f32_16x16x32_bf16 v[94:97], v[150:153], v[182:185], v[94:97]
	v_mfma_f32_16x16x32_bf16 v[86:89], v[158:161], v[182:185], v[86:89]
	v_mfma_f32_16x16x32_bf16 v[78:81], v[150:153], v[190:193], v[78:81]
	v_mfma_f32_16x16x32_bf16 v[70:73], v[158:161], v[190:193], v[70:73]
	v_mfma_f32_16x16x32_bf16 v[126:129], v[154:157], v[170:173], v[126:129]
	v_mfma_f32_16x16x32_bf16 v[118:121], v[162:165], v[170:173], v[118:121]
	v_mfma_f32_16x16x32_bf16 v[110:113], v[154:157], v[178:181], v[110:113]
	v_mfma_f32_16x16x32_bf16 v[102:105], v[162:165], v[178:181], v[102:105]
	v_mfma_f32_16x16x32_bf16 v[94:97], v[154:157], v[186:189], v[94:97]
	v_mfma_f32_16x16x32_bf16 v[86:89], v[162:165], v[186:189], v[86:89]
	v_mfma_f32_16x16x32_bf16 v[78:81], v[154:157], v[194:197], v[78:81]
	v_mfma_f32_16x16x32_bf16 v[70:73], v[162:165], v[194:197], v[70:73]
	s_setprio 0
	s_barrier
	ds_read_b128 v[166:169], v220 offset:16384
	ds_read_b128 v[170:173], v220 offset:17408
	ds_read_b128 v[174:177], v220 offset:18432
	ds_read_b128 v[178:181], v220 offset:19456
	ds_read_b128 v[182:185], v220 offset:20480
	ds_read_b128 v[186:189], v220 offset:21504
	ds_read_b128 v[190:193], v220 offset:22528
	ds_read_b128 v[194:197], v220 offset:23552
	s_add_i32 s62, s53, s12
	s_add_u32 s98, s46, s16
	s_addc_u32 s99, s47, s17
	s_mov_b32 m0, s62
	s_nop 0
	global_load_lds_dwordx4 v202, s[46:47]
	s_add_i32 m0, s62, 0x2000
	s_add_u32 s62, s46, 0x40000
	s_addc_u32 s63, s47, 0
	s_add_i32 s64, s54, s12
	global_load_lds_dwordx4 v198, s[46:47]
	s_mov_b32 m0, s64
	s_nop 0
	global_load_lds_dwordx4 v202, s[62:63]
	s_add_i32 m0, s64, 0x2000
	s_nop 0
	global_load_lds_dwordx4 v198, s[62:63]
	s_add_u32 s100, s48, s16
	s_addc_u32 s101, s49, s17
	s_mov_b32 m0, s40
	s_nop 0
	global_load_lds_dwordx4 v204, s[48:49]
	s_mov_b32 m0, s41
	s_nop 0
	global_load_lds_dwordx4 v200, s[48:49]
	s_waitcnt vmcnt(8)
	s_waitcnt lgkmcnt(0)
	s_barrier
	s_setprio 1
	s_waitcnt lgkmcnt(0)
	v_mfma_f32_16x16x32_bf16 v[66:69], v[134:137], v[166:169], v[66:69]
	v_mfma_f32_16x16x32_bf16 v[58:61], v[142:145], v[166:169], v[58:61]
	v_mfma_f32_16x16x32_bf16 v[50:53], v[134:137], v[174:177], v[50:53]
	v_mfma_f32_16x16x32_bf16 v[42:45], v[142:145], v[174:177], v[42:45]
	v_mfma_f32_16x16x32_bf16 v[34:37], v[134:137], v[182:185], v[34:37]
	v_mfma_f32_16x16x32_bf16 v[26:29], v[142:145], v[182:185], v[26:29]
	v_mfma_f32_16x16x32_bf16 v[18:21], v[134:137], v[190:193], v[18:21]
	v_mfma_f32_16x16x32_bf16 v[10:13], v[142:145], v[190:193], v[10:13]
	v_mfma_f32_16x16x32_bf16 v[66:69], v[138:141], v[170:173], v[66:69]
	v_mfma_f32_16x16x32_bf16 v[58:61], v[146:149], v[170:173], v[58:61]
	v_mfma_f32_16x16x32_bf16 v[50:53], v[138:141], v[178:181], v[50:53]
	v_mfma_f32_16x16x32_bf16 v[42:45], v[146:149], v[178:181], v[42:45]
	v_mfma_f32_16x16x32_bf16 v[34:37], v[138:141], v[186:189], v[34:37]
	v_mfma_f32_16x16x32_bf16 v[26:29], v[146:149], v[186:189], v[26:29]
	v_mfma_f32_16x16x32_bf16 v[18:21], v[138:141], v[194:197], v[18:21]
	v_mfma_f32_16x16x32_bf16 v[10:13], v[146:149], v[194:197], v[10:13]
	s_setprio 0
	s_setprio 1
	v_mfma_f32_16x16x32_bf16 v[62:65], v[150:153], v[166:169], v[62:65]
	v_mfma_f32_16x16x32_bf16 v[54:57], v[158:161], v[166:169], v[54:57]
	v_mfma_f32_16x16x32_bf16 v[46:49], v[150:153], v[174:177], v[46:49]
	v_mfma_f32_16x16x32_bf16 v[38:41], v[158:161], v[174:177], v[38:41]
	v_mfma_f32_16x16x32_bf16 v[30:33], v[150:153], v[182:185], v[30:33]
	v_mfma_f32_16x16x32_bf16 v[22:25], v[158:161], v[182:185], v[22:25]
	v_mfma_f32_16x16x32_bf16 v[14:17], v[150:153], v[190:193], v[14:17]
	v_mfma_f32_16x16x32_bf16 v[6:9], v[158:161], v[190:193], v[6:9]
	v_mfma_f32_16x16x32_bf16 v[62:65], v[154:157], v[170:173], v[62:65]
	v_mfma_f32_16x16x32_bf16 v[54:57], v[162:165], v[170:173], v[54:57]
	v_mfma_f32_16x16x32_bf16 v[46:49], v[154:157], v[178:181], v[46:49]
	v_mfma_f32_16x16x32_bf16 v[38:41], v[162:165], v[178:181], v[38:41]
	v_mfma_f32_16x16x32_bf16 v[30:33], v[154:157], v[186:189], v[30:33]
	v_mfma_f32_16x16x32_bf16 v[22:25], v[162:165], v[186:189], v[22:25]
	v_mfma_f32_16x16x32_bf16 v[14:17], v[154:157], v[194:197], v[14:17]
	v_mfma_f32_16x16x32_bf16 v[6:9], v[162:165], v[194:197], v[6:9]
	s_setprio 0
	s_barrier
	ds_read_b128 v[166:169], v220 offset:32768
	ds_read_b128 v[170:173], v220 offset:33792
	ds_read_b128 v[174:177], v220 offset:34816
	ds_read_b128 v[178:181], v220 offset:35840
	ds_read_b128 v[182:185], v220 offset:36864
	ds_read_b128 v[186:189], v220 offset:37888
	ds_read_b128 v[190:193], v220 offset:38912
	ds_read_b128 v[194:197], v220 offset:39936
	v_add_u32_e32 v134, 0x18000, v217
	v_add_u32_e32 v146, 0x1c000, v217
	ds_read_b128 v[150:153], v134
	ds_read_b128 v[154:157], v134 offset:1024
	ds_read_b128 v[158:161], v134 offset:2048
	ds_read_b128 v[162:165], v134 offset:3072
	ds_read_b128 v[134:137], v146
	ds_read_b128 v[138:141], v146 offset:1024
	ds_read_b128 v[142:145], v146 offset:2048
	ds_read_b128 v[146:149], v146 offset:3072
	s_add_i32 s62, 0, 0x18000
	s_add_i32 s63, 0, 0x1c000
	s_add_u32 s48, s48, 0x40000
	s_addc_u32 s49, s49, 0
	s_mov_b32 m0, s42
	s_nop 0
	global_load_lds_dwordx4 v204, s[48:49]
	s_mov_b32 m0, s43
	s_nop 0
	global_load_lds_dwordx4 v200, s[48:49]
	s_waitcnt vmcnt(8)
	s_waitcnt lgkmcnt(0)
	s_barrier
	s_setprio 1
	s_waitcnt lgkmcnt(0)
	v_mfma_f32_16x16x32_bf16 v[130:133], v[150:153], v[166:169], v[130:133]
	v_mfma_f32_16x16x32_bf16 v[122:125], v[158:161], v[166:169], v[122:125]
	v_mfma_f32_16x16x32_bf16 v[114:117], v[150:153], v[174:177], v[114:117]
	v_mfma_f32_16x16x32_bf16 v[106:109], v[158:161], v[174:177], v[106:109]
	v_mfma_f32_16x16x32_bf16 v[98:101], v[150:153], v[182:185], v[98:101]
	v_mfma_f32_16x16x32_bf16 v[90:93], v[158:161], v[182:185], v[90:93]
	v_mfma_f32_16x16x32_bf16 v[82:85], v[150:153], v[190:193], v[82:85]
	v_mfma_f32_16x16x32_bf16 v[74:77], v[158:161], v[190:193], v[74:77]
	v_mfma_f32_16x16x32_bf16 v[130:133], v[154:157], v[170:173], v[130:133]
	v_mfma_f32_16x16x32_bf16 v[122:125], v[162:165], v[170:173], v[122:125]
	v_mfma_f32_16x16x32_bf16 v[114:117], v[154:157], v[178:181], v[114:117]
	v_mfma_f32_16x16x32_bf16 v[106:109], v[162:165], v[178:181], v[106:109]
	v_mfma_f32_16x16x32_bf16 v[98:101], v[154:157], v[186:189], v[98:101]
	v_mfma_f32_16x16x32_bf16 v[90:93], v[162:165], v[186:189], v[90:93]
	v_mfma_f32_16x16x32_bf16 v[82:85], v[154:157], v[194:197], v[82:85]
	v_mfma_f32_16x16x32_bf16 v[74:77], v[162:165], v[194:197], v[74:77]
	s_setprio 0
	s_setprio 1
	v_mfma_f32_16x16x32_bf16 v[126:129], v[134:137], v[166:169], v[126:129]
	v_mfma_f32_16x16x32_bf16 v[118:121], v[142:145], v[166:169], v[118:121]
	v_mfma_f32_16x16x32_bf16 v[110:113], v[134:137], v[174:177], v[110:113]
	v_mfma_f32_16x16x32_bf16 v[102:105], v[142:145], v[174:177], v[102:105]
	v_mfma_f32_16x16x32_bf16 v[94:97], v[134:137], v[182:185], v[94:97]
	v_mfma_f32_16x16x32_bf16 v[86:89], v[142:145], v[182:185], v[86:89]
	v_mfma_f32_16x16x32_bf16 v[78:81], v[134:137], v[190:193], v[78:81]
	v_mfma_f32_16x16x32_bf16 v[70:73], v[142:145], v[190:193], v[70:73]
	v_mfma_f32_16x16x32_bf16 v[126:129], v[138:141], v[170:173], v[126:129]
	v_mfma_f32_16x16x32_bf16 v[118:121], v[146:149], v[170:173], v[118:121]
	v_mfma_f32_16x16x32_bf16 v[110:113], v[138:141], v[178:181], v[110:113]
	v_mfma_f32_16x16x32_bf16 v[102:105], v[146:149], v[178:181], v[102:105]
	v_mfma_f32_16x16x32_bf16 v[94:97], v[138:141], v[186:189], v[94:97]
	v_mfma_f32_16x16x32_bf16 v[86:89], v[146:149], v[186:189], v[86:89]
	v_mfma_f32_16x16x32_bf16 v[78:81], v[138:141], v[194:197], v[78:81]
	v_mfma_f32_16x16x32_bf16 v[70:73], v[146:149], v[194:197], v[70:73]
	s_setprio 0
	s_barrier
	ds_read_b128 v[190:193], v220 offset:49152
	ds_read_b128 v[194:197], v220 offset:50176
	ds_read_b128 v[182:185], v220 offset:51200
	ds_read_b128 v[186:189], v220 offset:52224
	ds_read_b128 v[174:177], v220 offset:53248
	ds_read_b128 v[178:181], v220 offset:54272
	ds_read_b128 v[166:169], v220 offset:55296
	ds_read_b128 v[170:173], v220 offset:56320
	s_add_i32 s48, s62, s12
	s_mov_b32 m0, s48
	s_nop 0
	global_load_lds_dwordx4 v202, s[98:99]
	s_add_i32 m0, s48, 0x2000
	s_add_u32 s46, s46, 0x40080
	s_addc_u32 s47, s47, 0
	s_add_i32 s48, s63, s12
	global_load_lds_dwordx4 v198, s[98:99]
	s_mov_b32 m0, s48
	s_andn2_b64 vcc, exec, s[30:31]
	global_load_lds_dwordx4 v202, s[46:47]
	s_add_i32 m0, s48, 0x2000
	s_nop 0
	global_load_lds_dwordx4 v198, s[46:47]
	s_mov_b32 m0, s51
	s_nop 0
	global_load_lds_dwordx4 v204, s[100:101]
	s_mov_b32 m0, s52
	s_nop 0
	global_load_lds_dwordx4 v200, s[100:101]
	s_waitcnt vmcnt(8)
	s_cbranch_vccnz .LBB0_1765
	s_and_saveexec_b64 s[30:31], s[4:5]
	s_cbranch_execz .LBB0_1764
	v_mov_b32_e32 v222, v3
	v_mov_b32_e32 v223, v4
	v_mov_b32_e32 v224, v2
	v_mov_b32_e32 v225, v5
	v_pk_add_f32 v[222:223], v[222:223], v[224:225]
	s_nop 0
	v_add_f32_e32 v222, v222, v223
	v_fmamk_f32 v222, v222, 0x3a800000, v221
	ds_write_b32 v219, v222
	s_branch .LBB0_1764
